# blocked layout also for attention/hyena mix (out-proj A operand)
# speedup vs baseline: 1.1994x; 1.0110x over previous
; DI void ytrans_loop(const Params& p, char* smem) {
;     ...
;   for (;;) {
;     const int itn = it + gridDim.x;
;     const bool has = itn < 2048;
;     if (has) YT_LOAD(itn, n0, n1)
;     {
;       const unsigned pa[4] = {w0.x, w0.y, w0.z, w0.w}, pb[4] = {w1.x, w1.y, w1.z, w1.w};
; #pragma unroll
;       for (int e = 0; e < 8; ++e) {
;         sT[(t8 * 8 + e) * 66 + cc0] = (bf16_t)((pa[e >> 1] >> ((e & 1) * 16)) & 0xffff);
;         sT[(t8 * 8 + e) * 66 + cc0 + 32] = (bf16_t)((pb[e >> 1] >> ((e & 1) * 16)) & 0xffff);
;       }
;     }
;     __syncthreads();
;     {
;       const int b = it >> 8, tt0 = ((it >> 2) & 63) * 64, c0 = (it & 3) * 64;
;       bf16_t* MIX = (bf16_t*)(p.ws + OFF_U) + ((size_t)b * SEQ + tt0) * D + c0;
; #pragma unroll
;       for (int i = 0; i < 2; ++i) {
;         int id = tid + 256 * i, tt = id >> 3, c8 = id & 7;
;         const unsigned* sp = (const unsigned*)(sT + tt * 66 + c8 * 8);
;         uint4 w; w.x = sp[0]; w.y = sp[1]; w.z = sp[2]; w.w = sp[3];
;         *(uint4*)(MIX + (size_t)tt * D + c8 * 8) = w;
;       }
;     }
;     __syncthreads();
;     if (!has) break;
;     it = itn; w0 = n0; w1 = n1;
;   }
.LBB0_1448:
	s_ashr_i32 s28, s13, 8
	s_ashr_i32 s29, s28, 31
	s_and_b32 s13, s10, 0x3f0000
	s_and_b32 s36, s11, 0xc0
	s_lshl_b64 s[28:29], s[28:29], 23
	s_add_u32 s28, s24, s28
	s_addc_u32 s29, s25, s29
	s_lshl_b32 s13, s13, 1
	s_add_u32 s13, s28, s13
	s_waitcnt vmcnt(1)
	ds_write_b16 v17, v12
	s_waitcnt vmcnt(0)
	ds_write_b16 v17, v8 offset:64
	ds_write_b16_d16_hi v17, v12 offset:132
	ds_write_b16_d16_hi v17, v8 offset:196
	ds_write_b16 v17, v13 offset:264
	ds_write_b16 v17, v9 offset:328
	ds_write_b16_d16_hi v17, v13 offset:396
	ds_write_b16_d16_hi v17, v9 offset:460
	ds_write_b16 v17, v14 offset:528
	ds_write_b16 v17, v10 offset:592
	ds_write_b16_d16_hi v17, v14 offset:660
	ds_write_b16_d16_hi v17, v10 offset:724
	ds_write_b16 v17, v15 offset:792
	ds_write_b16 v17, v11 offset:856
	ds_write_b16_d16_hi v17, v15 offset:924
	ds_write_b16_d16_hi v17, v11 offset:988
	s_waitcnt lgkmcnt(0)
	s_barrier
	s_addc_u32 s29, s29, 0
	s_lshl_b32 s28, s36, 1
	ds_read2_b32 v[8:9], v26 offset1:1
	ds_read2_b32 v[10:11], v26 offset0:2 offset1:3
	s_add_u32 s28, s13, s28
	s_addc_u32 s29, s29, 0
	v_lshl_add_u64 v[12:13], s[28:29], 0, v[140:141]
	v_lshl_add_u64 v[14:15], v[12:13], 0, v[22:23]
	s_waitcnt lgkmcnt(0)
	v_subrev_u32_e32 v242, s24, v14
	v_lshrrev_b32_e32 v243, 11, v242
	v_and_b32_e32 v242, 0x7ff, v242
	v_lshrrev_b32_e32 v244, 6, v242
	v_mul_u32_u24_e32 v244, 0x8800, v244
	v_add_u32_e32 v244, v244, v243
	v_and_b32_e32 v242, 63, v242
	v_lshl_add_u32 v238, v244, 6, v242
	v_mov_b32_e32 v239, 0
	v_lshl_add_u64 v[238:239], v[238:239], 0, s[24:25]
	global_store_dwordx4 v[238:239], v[8:11], off
	ds_read2_b32 v[8:9], v27 offset1:1
	ds_read2_b32 v[10:11], v27 offset0:2 offset1:3
	v_readlane_b32 s13, v234, 16
	s_add_i32 s11, s11, s13
	v_readlane_b32 s13, v234, 18
	v_lshl_add_u64 v[12:13], v[12:13], 0, v[24:25]
	s_add_i32 s10, s10, s13
	v_readlane_b32 s13, v234, 19
	s_waitcnt lgkmcnt(0)
	v_subrev_u32_e32 v242, s24, v12
	v_lshrrev_b32_e32 v243, 11, v242
	v_and_b32_e32 v242, 0x7ff, v242
	v_lshrrev_b32_e32 v244, 6, v242
	v_mul_u32_u24_e32 v244, 0x8800, v244
	v_add_u32_e32 v244, v244, v243
	v_and_b32_e32 v242, 63, v242
	v_lshl_add_u32 v238, v244, 6, v242
	v_mov_b32_e32 v239, 0
	v_lshl_add_u64 v[238:239], v[238:239], 0, s[24:25]
	global_store_dwordx4 v[238:239], v[8:11], off
	s_add_i32 s7, s7, s13
	v_readlane_b32 s13, v234, 20
	v_mov_b64_e32 v[10:11], v[2:3]
	v_mov_b64_e32 v[14:15], v[6:7]
	s_add_i32 s6, s6, s13
	s_andn2_b64 vcc, exec, s[0:1]
	v_mov_b64_e32 v[8:9], v[0:1]
	v_mov_b64_e32 v[12:13], v[4:5]
	s_mov_b32 s13, s12
	s_barrier
	s_cbranch_vccz .LBB0_1487

; DI unsigned pack2(float lo, float hi) { f32x2_t v = {lo, hi}; bf16x2_t r = __builtin_convertvector(v, bf16x2_t); return __builtin_bit_cast(unsigned, r); }
; DI float xhalf_sum(float x) { auto r = __builtin_amdgcn_permlane32_swap(__float_as_uint(x), __float_as_uint(x), false, false); return __uint_as_float(r[0]) + __uint_as_float(r[1]); }
; template <int DQK>
; DI void attn_item(const bf16_t* __restrict__ Q, const bf16_t* __restrict__ Kp, const bf16_t* __restrict__ Vt, int q0, int nkeys,
;                   bf16_t* __restrict__ mix, int colbase, int b, char* smem) {
;     ...
;   l = xhalf_sum(l);
;   const float inv = 1.0f / l;
;   const int kp = q0 + wave * 32 + r;
;   bf16_t* orow = mix + (size_t)row_of(b, kp) * D + colbase;
; #pragma unroll
;   for (int g = 0; g < 4; ++g) {
;     uint2 w0, w1;
;     w0.x = pack2(o0[4 * g] * inv, o0[4 * g + 1] * inv); w0.y = pack2(o0[4 * g + 2] * inv, o0[4 * g + 3] * inv);
;     w1.x = pack2(o1[4 * g] * inv, o1[4 * g + 1] * inv); w1.y = pack2(o1[4 * g + 2] * inv, o1[4 * g + 3] * inv);
;     *(uint2*)(orow + 8 * g + 4 * h) = w0;
;     *(uint2*)(orow + 32 + 8 * g + 4 * h) = w1;
;   }
.LBB0_1452:
	v_add_f32_e32 v32, v129, v32
	v_div_scale_f32 v33, s[36:37], v32, v32, 1.0
	v_rcp_f32_e32 v34, v33
	s_movk_i32 s11, 0x100
	v_cmp_gt_i32_e32 vcc, s11, v128
	s_lshl_b32 s10, s29, 6
	v_fma_f32 v37, -v33, v34, 1.0
	v_cndmask_b32_e64 v35, 12, 8, vcc
	v_cndmask_b32_e32 v36, v210, v211, vcc
	v_fmac_f32_e32 v34, v37, v34
	v_div_scale_f32 v37, vcc, 1.0, v32, 1.0
	v_mul_f32_e32 v38, v37, v34
	v_fma_f32 v39, -v33, v38, v37
	v_fmac_f32_e32 v38, v39, v34
	v_lshlrev_b32_e64 v35, v35, s28
	v_fma_f32 v33, -v33, v38, v37
	v_div_fmas_f32 v33, v33, v34, v38
	v_add3_u32 v34, v36, v128, v35
	v_ashrrev_i32_e32 v35, 31, v34
	v_lshlrev_b64 v[34:35], 11, v[34:35]
	v_div_fixup_f32 v32, v33, v32, 1.0
	v_lshl_add_u64 v[34:35], s[24:25], 0, v[34:35]
	s_ashr_i32 s11, s10, 31
	v_lshl_add_u64 v[34:35], s[10:11], 1, v[34:35]
	v_pk_mul_f32 v[0:1], v[32:33], v[0:1] op_sel_hi:[0,1]
	v_pk_mul_f32 v[2:3], v[32:33], v[2:3] op_sel_hi:[0,1]
	v_lshl_add_u64 v[36:37], v[34:35], 0, s[6:7]
	v_lshlrev_b64 v[38:39], 1, v[140:141]
	v_cvt_pk_bf16_f32 v0, v0, v1
	v_cvt_pk_bf16_f32 v1, v2, v3
	v_pk_mul_f32 v[2:3], v[32:33], v[16:17] op_sel_hi:[0,1]
	v_pk_mul_f32 v[16:17], v[32:33], v[18:19] op_sel_hi:[0,1]
	v_lshl_add_u64 v[36:37], v[36:37], 0, v[38:39]
	v_lshl_add_u64 v[34:35], v[34:35], 0, s[0:1]
	v_cvt_pk_bf16_f32 v2, v2, v3
	v_cvt_pk_bf16_f32 v3, v16, v17
	v_lshl_add_u64 v[34:35], v[34:35], 0, v[38:39]
	v_subrev_u32_e32 v242, s24, v36
	v_lshrrev_b32_e32 v243, 11, v242
	v_and_b32_e32 v242, 0x7ff, v242
	v_lshrrev_b32_e32 v244, 6, v242
	v_mul_u32_u24_e32 v244, 0x8800, v244
	v_add_u32_e32 v244, v244, v243
	v_and_b32_e32 v242, 63, v242
	v_lshl_add_u32 v238, v244, 6, v242
	v_mov_b32_e32 v239, 0
	v_lshl_add_u64 v[238:239], v[238:239], 0, s[24:25]
	v_subrev_u32_e32 v242, s24, v34
	v_lshrrev_b32_e32 v243, 11, v242
	v_and_b32_e32 v242, 0x7ff, v242
	v_lshrrev_b32_e32 v244, 6, v242
	v_mul_u32_u24_e32 v244, 0x8800, v244
	v_add_u32_e32 v244, v244, v243
	v_and_b32_e32 v242, 63, v242
	v_lshl_add_u32 v240, v244, 6, v242
	v_mov_b32_e32 v241, 0
	v_lshl_add_u64 v[240:241], v[240:241], 0, s[24:25]
	global_store_dwordx2 v[238:239], v[0:1], off
	global_store_dwordx2 v[240:241], v[2:3], off
	v_pk_mul_f32 v[0:1], v[32:33], v[4:5] op_sel_hi:[0,1]
	v_pk_mul_f32 v[2:3], v[32:33], v[6:7] op_sel_hi:[0,1]
	v_cvt_pk_bf16_f32 v0, v0, v1
	v_cvt_pk_bf16_f32 v1, v2, v3
	v_pk_mul_f32 v[2:3], v[32:33], v[20:21] op_sel_hi:[0,1]
	v_pk_mul_f32 v[4:5], v[32:33], v[22:23] op_sel_hi:[0,1]
	v_cvt_pk_bf16_f32 v2, v2, v3
	v_cvt_pk_bf16_f32 v3, v4, v5
	global_store_dwordx2 v[238:239], v[0:1], off offset:16
	global_store_dwordx2 v[240:241], v[2:3], off offset:16
	v_pk_mul_f32 v[0:1], v[32:33], v[8:9] op_sel_hi:[0,1]
	v_pk_mul_f32 v[2:3], v[32:33], v[10:11] op_sel_hi:[0,1]
	v_cvt_pk_bf16_f32 v0, v0, v1
	v_cvt_pk_bf16_f32 v1, v2, v3
	v_pk_mul_f32 v[2:3], v[32:33], v[24:25] op_sel_hi:[0,1]
	v_pk_mul_f32 v[4:5], v[32:33], v[26:27] op_sel_hi:[0,1]
	v_cvt_pk_bf16_f32 v2, v2, v3
	v_cvt_pk_bf16_f32 v3, v4, v5
	global_store_dwordx2 v[238:239], v[0:1], off offset:32
	global_store_dwordx2 v[240:241], v[2:3], off offset:32
	v_pk_mul_f32 v[0:1], v[32:33], v[12:13] op_sel_hi:[0,1]
	v_pk_mul_f32 v[2:3], v[32:33], v[14:15] op_sel_hi:[0,1]
	v_cvt_pk_bf16_f32 v0, v0, v1
	v_cvt_pk_bf16_f32 v1, v2, v3
	v_pk_mul_f32 v[2:3], v[32:33], v[28:29] op_sel_hi:[0,1]
	v_pk_mul_f32 v[4:5], v[32:33], v[30:31] op_sel_hi:[0,1]
	s_add_i32 s13, s13, s26
	v_cvt_pk_bf16_f32 v2, v2, v3
	v_cvt_pk_bf16_f32 v3, v4, v5
	s_cmp_ge_i32 s13, s12
	global_store_dwordx2 v[238:239], v[0:1], off offset:48
	global_store_dwordx2 v[240:241], v[2:3], off offset:48
	s_cbranch_scc1 .LBB0_1446

; DI int get_tid() { int t = threadIdx.x; asm volatile("" : "+v"(t)); return t; }
; DI void phase_attn(const Params& p, int layer, char* smem) {
;     ...
;   if (layer == 0) {
;     const bf16_t* YC = (const bf16_t*)(p.ws + OFF_H);
;     bf16_t* MIX = (bf16_t*)(p.ws + OFF_U);
;     for (int i = blockIdx.x * 256 + get_tid(); i < NCTXR * 32; i += gridDim.x * 256) {
;       int rr = i >> 5, c8 = i & 31;
;       *(uint4*)(MIX + (size_t)(NLAT + rr) * D + c8 * 8) = *(const uint4*)(YC + (size_t)rr * 256 + c8 * 8);
;     }
.LBB0_1490:
	v_ashrrev_i32_e32 v2, 5, v0
	v_ashrrev_i32_e32 v3, 31, v2
	v_lshlrev_b64 v[4:5], 9, v[2:3]
	v_and_b32_e32 v6, 0xf8, v1
	v_lshlrev_b64 v[2:3], 11, v[2:3]
	v_lshlrev_b32_e32 v140, 1, v6
	v_lshl_add_u64 v[2:3], s[24:25], 0, v[2:3]
	v_lshl_add_u64 v[4:5], s[74:75], 0, v[4:5]
	v_lshl_add_u64 v[2:3], v[2:3], 0, v[140:141]
	v_lshl_add_u64 v[4:5], v[4:5], 0, v[140:141]
	v_add_co_u32_e32 v6, vcc, 0x4000000, v2
	v_add_u32_e32 v0, s55, v0
	s_nop 0
	v_addc_co_u32_e32 v7, vcc, 0, v3, vcc
	global_load_dwordx4 v[2:5], v[4:5], off
	s_mov_b32 s10, 0xffff
	v_cmp_lt_i32_e32 vcc, s10, v0
	v_add_u32_e32 v1, s11, v1
	s_or_b64 s[6:7], vcc, s[6:7]
	s_waitcnt vmcnt(0)
	v_subrev_u32_e32 v242, s24, v6
	v_lshrrev_b32_e32 v243, 11, v242
	v_and_b32_e32 v242, 0x7ff, v242
	v_lshrrev_b32_e32 v244, 6, v242
	v_mul_u32_u24_e32 v244, 0x8800, v244
	v_add_u32_e32 v244, v244, v243
	v_and_b32_e32 v242, 63, v242
	v_lshl_add_u32 v238, v244, 6, v242
	v_mov_b32_e32 v239, 0
	v_lshl_add_u64 v[238:239], v[238:239], 0, s[24:25]
	global_store_dwordx4 v[238:239], v[2:5], off
	s_andn2_b64 exec, exec, s[6:7]
	s_cbranch_execnz .LBB0_1490

; DI int get_tid() { int t = threadIdx.x; asm volatile("" : "+v"(t)); return t; }
; template <int EPI>
; DI void gemm_phase(const Params& p, int layer, const bf16_t* __restrict__ A, int lda, const bf16_t* __restrict__ Bt, int ldb, int K, int MT, int NT,
;                    char* smem, bool rev = false) {
;   bf16_t* sA = (bf16_t*)smem;
;   bf16_t* sB = sA + 2 * 128 * LDT;
;   const int tid = get_tid(), lane = tid & 63, wave = tid >> 6, wr = wave >> 1, wc = wave & 1;
;   const int total = MT * NT;
;   int t = rev ? (int)(gridDim.x - 1 - blockIdx.x) : (int)blockIdx.x;
;   if (t >= total) return;
;   uint4 pa0, pa1, pa2, pa3, pb0, pb1, pb2, pb3, qa0, qa1, qa2, qa3, qb0, qb1, qb2, qb3;
;   const int lr = tid >> 3, lc = (tid & 7) * 8;
;   const int nk = K >> 6;
;   const int soff = lr * LDT + lc;
;   const int aoff = (wr * 64 + (lane & 31)) * LDT + (lane >> 5) * 8;
;   const int boff = (wc * 64 + (lane & 31)) * LDT + (lane >> 5) * 8;
;   int mt, nt; tile_map(t, MT, NT, mt, nt);
;   int m0 = mt * 128, n0 = nt * 128;
;   const bf16_t* Agl = A + (size_t)(m0 + lr) * lda + lc;
;   const bf16_t* Bgl = Bt + (size_t)(n0 + lr) * ldb + lc;
; __global__ void __launch_bounds__(THREADS, 2) fwd_megakernel(Params p) {
;     ...
;     gemm_phase<EPI_RES1>(p, layer, (const bf16_t*)(p.ws + OFF_U), D, wl + W_OUT, D, D, MT_RES, D / 128, smem);
.Lmg_par_3:
	s_mov_b32 s54, s24
	s_mov_b32 s55, s25
	s_movk_i32 s58, 0x40
	s_movk_i32 s59, 0x40
	s_mov_b32 s81, 0x220000
	s_mov_b32 s48, 0x10000
	s_movk_i32 s60, 32
	s_movk_i32 s62, 8
	s_movk_i32 s69, 8192
	s_add_u32 s56, s56, 0x3c0000
	s_addc_u32 s57, s57, 0
	s_branch .Lmg_pare_6

; template <int DQK>
; DI void attn_item(const bf16_t* __restrict__ Q, const bf16_t* __restrict__ Kp, const bf16_t* __restrict__ Vt, int q0, int nkeys,
;                   bf16_t* __restrict__ mix, int colbase, int b, char* smem) {
;     ...
;   bf16x8 qf[NSTEP];
;   {
;     const bf16_t* qr = Q + (size_t)(q0 + wave * 32 + r) * DQK + 8 * h;
; #pragma unroll
;     for (int s = 0; s < NSTEP; ++s) qf[s] = *(const bf16x8*)(qr + 16 * s);
;   }
;   const int kid0 = tid, kid1 = tid + 256, kid2 = tid + 512;
;   const int kgo0 = (kid0 / KCH) * DQK + (kid0 % KCH) * 8, kgo1 = (kid1 / KCH) * DQK + (kid1 % KCH) * 8, kgo2 = (kid2 / KCH) * DQK + (kid2 % KCH) * 8;
;   const int kso0 = (kid0 / KCH) * KROW + (kid0 % KCH) * 8, kso1 = (kid1 / KCH) * KROW + (kid1 % KCH) * 8, kso2 = (kid2 / KCH) * KROW + (kid2 % KCH) * 8;
;   const int vrow0 = tid >> 3, vcc = (tid & 7) * 8;
;   const bf16_t* Vg0 = Vt + (size_t)vrow0 * NKEY + vcc;
;   const bf16_t* Vg1 = Vt + (size_t)(vrow0 + 32) * NKEY + vcc;
;   const int vso0 = vrow0 * VROW + vcc, vso1 = (vrow0 + 32) * VROW + vcc;
;   uint4 pk0, pk1, pk2, pv0, pv1, qk0, qk1, qk2, qv0, qv1;
;   pk2 = make_uint4(0, 0, 0, 0); qk2 = pk2;
;     ...
;   f32x16 o0, o1;
; #pragma unroll
;   for (int i = 0; i < 16; ++i) { o0[i] = 0.f; o1[i] = 0.f; }
;   float m = -1e30f, l = 0.f;
; DI void attn_dispatch(const Params& p, int type, int b, int hd, int qb, char* smem) {
;   bf16_t* MIX = (bf16_t*)(p.ws + OFF_U);
;   const int nkeys = qb < 2 ? CTX : NKEY;
;   if (type == 0) {
;     const bf16_t* Q = (const bf16_t*)(p.ws + OFF_QG) + (size_t)(b * 6 + hd) * NKEY * 64;
;     const bf16_t* K = (const bf16_t*)(p.ws + OFF_KG) + (size_t)(b * 2 + hd / 3) * NKEY * 64;
;     const bf16_t* V = (const bf16_t*)(p.ws + OFF_VGT) + (size_t)(b * 2 + hd / 3) * 64 * NKEY;
;     attn_item<64>(Q, K, V, qb * 128, nkeys, MIX, 256 + hd * 64, b, smem);
.Lat_ty_1:
	s_mul_i32 s54, s10, 43
	s_lshr_b32 s54, s54, 8
	s_mul_i32 s11, s54, 6
	s_sub_u32 s55, s10, s11
	s_lshl_b32 s11, s54, 12
	s_add_u32 s11, s11, s56
	s_sub_u32 s11, s11, 256
	s_lshl_b32 s28, s57, 5
	s_add_u32 s11, s11, s28
	v_add_u32_e32 v252, s11, v253
	v_lshlrev_b32_e32 v252, 6, v252
	v_lshl_add_u32 v252, v140, 3, v252
	s_cmp_eq_u32 s53, 1
	s_cbranch_scc1 .Lat_mla_2
	s_mul_i32 s11, s54, 6
	s_add_u32 s11, s11, s55
	s_mul_i32 s28, s11, 0x88000
	s_add_u32 s28, s28, 0x7f80000
	s_add_u32 s58, s24, s28
	s_addc_u32 s59, s25, 0
	s_mul_i32 s29, s55, 43
	s_lshr_b32 s29, s29, 7
	s_lshl_b32 s11, s54, 1
	s_add_u32 s11, s11, s29
	s_mul_i32 s28, s11, 0x88000
	s_add_u32 s28, s28, 0x9900000
	s_add_u32 s60, s24, s28
	s_addc_u32 s61, s25, 0
	s_mul_i32 s28, s11, 0x88000
	s_add_u32 s28, s28, 0xa180000
	s_add_u32 s62, s24, s28
	s_addc_u32 s63, s25, 0
	s_lshl_b32 s28, s55, 1
	s_add_u32 s28, s28, 8
	s_mul_i32 s28, s28, 0x220000
	v_add_u32_e32 v252, s28, v252
	s_lshl_b32 s28, s57, 5
	s_add_u32 s28, s28, s56
	v_add_u32_e32 v251, s28, v253
	s_movk_i32 s29, 128
	v_mul_lo_u32 v251, v251, s29
	v_lshl_add_u32 v251, v140, 4, v251
	s_movk_i32 s29, 144
	v_mul_lo_u32 v238, v253, s29
	v_lshl_add_u32 v238, v140, 4, v238
	s_movk_i32 s29, 136
	v_mul_lo_u32 v239, v253, s29
	v_lshl_add_u32 v239, v140, 3, v239
	v_add_u32_e32 v240, 0x1100, v239
	v_mov_b32_e32 v225, v143
	v_lshrrev_b32_e32 v226, 3, v225
	v_and_b32_e32 v227, 7, v225
	s_movk_i32 s29, 128
	v_mul_lo_u32 v246, v226, s29
	v_lshl_add_u32 v246, v227, 4, v246
	s_movk_i32 s29, 144
	v_mul_lo_u32 v241, v226, s29
	v_lshl_add_u32 v241, v227, 4, v241
	v_add_u32_e32 v225, 256, v143
	v_lshrrev_b32_e32 v226, 3, v225
	v_and_b32_e32 v227, 7, v225
	s_movk_i32 s29, 128
	v_mul_lo_u32 v247, v226, s29
	v_lshl_add_u32 v247, v227, 4, v247
	s_movk_i32 s29, 144
	v_mul_lo_u32 v242, v226, s29
	v_lshl_add_u32 v242, v227, 4, v242
	v_lshrrev_b32_e32 v226, 3, v143
	v_and_b32_e32 v227, 7, v143
	s_movk_i32 s29, 8704
	v_mul_lo_u32 v249, v226, s29
	v_lshl_add_u32 v249, v227, 4, v249
	v_add_u32_e32 v250, 0x44000, v249
	s_movk_i32 s29, 136
	v_mul_lo_u32 v244, v226, s29
	v_lshl_add_u32 v244, v227, 4, v244
	v_add_u32_e32 v245, 0x1100, v244
	s_barrier
	global_load_dwordx4 v[112:115], v251, s[58:59] offset:0
	global_load_dwordx4 v[116:119], v251, s[58:59] offset:32
	global_load_dwordx4 v[120:123], v251, s[58:59] offset:64
	global_load_dwordx4 v[124:127], v251, s[58:59] offset:96
	s_mov_b32 s1, 0
	s_min_u32 s0, s1, 67
	s_mul_i32 s0, s0, 0x2000
	s_add_u32 s64, s60, s0
	s_addc_u32 s65, s61, 0
	s_min_u32 s0, s1, 67
	s_lshl_b32 s0, s0, 7
	s_add_u32 s66, s62, s0
	s_addc_u32 s67, s63, 0
	global_load_dwordx4 v[176:179], v246, s[64:65]
	global_load_dwordx4 v[180:183], v247, s[64:65]
	global_load_dwordx4 v[212:215], v249, s[66:67]
	global_load_dwordx4 v[216:219], v250, s[66:67]
	s_waitcnt vmcnt(0)
	ds_write_b128 v241, v[176:179] offset:0
	ds_write_b128 v242, v[180:183] offset:0
	ds_write_b64 v244, v[212:213] offset:18432
	ds_write_b64 v244, v[214:215] offset:18440
	ds_write_b64 v245, v[216:217] offset:18432
	ds_write_b64 v245, v[218:219] offset:18440
	s_mov_b32 s1, 1
	s_min_u32 s0, s1, 67
	s_mul_i32 s0, s0, 0x2000
	s_add_u32 s64, s60, s0
	s_addc_u32 s65, s61, 0
	s_min_u32 s0, s1, 67
	s_lshl_b32 s0, s0, 7
	s_add_u32 s66, s62, s0
	s_addc_u32 s67, s63, 0
	global_load_dwordx4 v[176:179], v246, s[64:65]
	global_load_dwordx4 v[180:183], v247, s[64:65]
	s_waitcnt vmcnt(0)
	ds_write_b128 v241, v[176:179] offset:9216
	ds_write_b128 v242, v[180:183] offset:9216
	s_mov_b32 s1, 2
	s_mov_b32 s10, 1
	s_min_u32 s0, s1, 67
	s_mul_i32 s0, s0, 0x2000
	s_add_u32 s64, s60, s0
	s_addc_u32 s65, s61, 0
	s_min_u32 s0, s10, 67
	s_lshl_b32 s0, s0, 7
	s_add_u32 s66, s62, s0
	s_addc_u32 s67, s63, 0
	global_load_dwordx4 v[176:179], v246, s[64:65]
	global_load_dwordx4 v[180:183], v247, s[64:65]
	global_load_dwordx4 v[212:215], v249, s[66:67]
	global_load_dwordx4 v[216:219], v250, s[66:67]
	v_mov_b32_e32 v0, 0
	v_mov_b32_e32 v1, 0
	v_mov_b32_e32 v2, 0
	v_mov_b32_e32 v3, 0
	v_mov_b32_e32 v4, 0
	v_mov_b32_e32 v5, 0
	v_mov_b32_e32 v6, 0
	v_mov_b32_e32 v7, 0
	v_mov_b32_e32 v8, 0
	v_mov_b32_e32 v9, 0
	v_mov_b32_e32 v10, 0
	v_mov_b32_e32 v11, 0
	v_mov_b32_e32 v12, 0
	v_mov_b32_e32 v13, 0
	v_mov_b32_e32 v14, 0
	v_mov_b32_e32 v15, 0
	v_mov_b32_e32 v16, 0
	v_mov_b32_e32 v17, 0
	v_mov_b32_e32 v18, 0
	v_mov_b32_e32 v19, 0
	v_mov_b32_e32 v20, 0
	v_mov_b32_e32 v21, 0
	v_mov_b32_e32 v22, 0
	v_mov_b32_e32 v23, 0
	v_mov_b32_e32 v24, 0
	v_mov_b32_e32 v25, 0
	v_mov_b32_e32 v26, 0
	v_mov_b32_e32 v27, 0
	v_mov_b32_e32 v28, 0
	v_mov_b32_e32 v29, 0
	v_mov_b32_e32 v30, 0
	v_mov_b32_e32 v31, 0
	v_mov_b32_e32 v221, 0
	s_waitcnt lgkmcnt(0)
	s_barrier
	ds_read_b128 v[144:147], v238 offset:0
	ds_read_b128 v[148:151], v238 offset:4608
	ds_read_b128 v[152:155], v238 offset:32
	ds_read_b128 v[156:159], v238 offset:4640
	s_waitcnt lgkmcnt(3)
	v_mfma_f32_32x32x16_bf16 v[32:47], v[144:147], v[112:115], 0
	ds_read_b128 v[144:147], v238 offset:64
	s_waitcnt lgkmcnt(3)
	v_mfma_f32_32x32x16_bf16 v[48:63], v[148:151], v[112:115], 0
	ds_read_b128 v[148:151], v238 offset:4672
	s_waitcnt lgkmcnt(3)
	v_mfma_f32_32x32x16_bf16 v[32:47], v[152:155], v[116:119], v[32:47]
	ds_read_b128 v[152:155], v238 offset:96
	s_waitcnt lgkmcnt(3)
	v_mfma_f32_32x32x16_bf16 v[48:63], v[156:159], v[116:119], v[48:63]
	ds_read_b128 v[156:159], v238 offset:4704
	s_waitcnt lgkmcnt(3)
	v_mfma_f32_32x32x16_bf16 v[32:47], v[144:147], v[120:123], v[32:47]
	s_waitcnt lgkmcnt(2)
	v_mfma_f32_32x32x16_bf16 v[48:63], v[148:151], v[120:123], v[48:63]
	s_waitcnt lgkmcnt(1)
	v_mfma_f32_32x32x16_bf16 v[32:47], v[152:155], v[124:127], v[32:47]
	s_waitcnt lgkmcnt(0)
	v_mfma_f32_32x32x16_bf16 v[48:63], v[156:159], v[124:127], v[48:63]
	s_waitcnt lgkmcnt(0)
	s_barrier
	s_nop 7
	s_nop 3
	v_max3_f32 v223, v32, v33, v34
	v_max3_f32 v224, v40, v41, v42
	v_max3_f32 v225, v48, v49, v50
	v_max3_f32 v226, v56, v57, v58
	v_max3_f32 v223, v223, v35, v36
	v_max3_f32 v224, v224, v43, v44
	v_max3_f32 v225, v225, v51, v52
	v_max3_f32 v226, v226, v59, v60
	v_max3_f32 v223, v223, v37, v38
	v_max3_f32 v224, v224, v45, v46
	v_max3_f32 v225, v225, v53, v54
	v_max3_f32 v226, v226, v61, v62
	v_max_f32_e32 v223, v223, v39
	v_max_f32_e32 v224, v224, v47
	v_max_f32_e32 v225, v225, v55
	v_max_f32_e32 v226, v226, v63
	v_max3_f32 v222, v223, v224, v225
	v_max_f32_e32 v222, v222, v226
	v_mov_b32_e32 v227, v222
	s_nop 1
	v_permlane32_swap_b32_e32 v222, v227
	v_max_f32_e32 v222, v222, v227
	v_sub_f32_e32 v32, v32, v222
	v_sub_f32_e32 v33, v33, v222
	v_sub_f32_e32 v34, v34, v222
	v_sub_f32_e32 v35, v35, v222
	v_sub_f32_e32 v36, v36, v222
	v_sub_f32_e32 v37, v37, v222
	v_sub_f32_e32 v38, v38, v222
	v_sub_f32_e32 v39, v39, v222
	v_sub_f32_e32 v40, v40, v222
	v_sub_f32_e32 v41, v41, v222
	v_sub_f32_e32 v42, v42, v222
	v_sub_f32_e32 v43, v43, v222
	v_sub_f32_e32 v44, v44, v222
	v_sub_f32_e32 v45, v45, v222
	v_sub_f32_e32 v46, v46, v222
	v_sub_f32_e32 v47, v47, v222
	v_sub_f32_e32 v48, v48, v222
	v_sub_f32_e32 v49, v49, v222
	v_sub_f32_e32 v50, v50, v222
	v_sub_f32_e32 v51, v51, v222
	v_sub_f32_e32 v52, v52, v222
	v_sub_f32_e32 v53, v53, v222
	v_sub_f32_e32 v54, v54, v222
	v_sub_f32_e32 v55, v55, v222
	v_sub_f32_e32 v56, v56, v222
	v_sub_f32_e32 v57, v57, v222
	v_sub_f32_e32 v58, v58, v222
	v_sub_f32_e32 v59, v59, v222
	v_sub_f32_e32 v60, v60, v222
	v_sub_f32_e32 v61, v61, v222
	v_sub_f32_e32 v62, v62, v222
	v_sub_f32_e32 v63, v63, v222
	v_sub_f32_e32 v160, 0, v222
	v_sub_f32_e32 v161, 0, v222
	v_sub_f32_e32 v162, 0, v222
	v_sub_f32_e32 v163, 0, v222
	v_sub_f32_e32 v164, 0, v222
	v_sub_f32_e32 v165, 0, v222
	v_sub_f32_e32 v166, 0, v222
	v_sub_f32_e32 v167, 0, v222
	v_sub_f32_e32 v168, 0, v222
	v_sub_f32_e32 v169, 0, v222
	v_sub_f32_e32 v170, 0, v222
	v_sub_f32_e32 v171, 0, v222
	v_sub_f32_e32 v172, 0, v222
	v_sub_f32_e32 v173, 0, v222
	v_sub_f32_e32 v174, 0, v222
	v_sub_f32_e32 v175, 0, v222
	s_mov_b32 s69, 0
	s_mov_b32 s68, 0

; DI unsigned pack2(float lo, float hi) { f32x2_t v = {lo, hi}; bf16x2_t r = __builtin_convertvector(v, bf16x2_t); return __builtin_bit_cast(unsigned, r); }
; DI float xhalf_sum(float x) { auto r = __builtin_amdgcn_permlane32_swap(__float_as_uint(x), __float_as_uint(x), false, false); return __uint_as_float(r[0]) + __uint_as_float(r[1]); }
; template <int DQK>
; DI void attn_item(const bf16_t* __restrict__ Q, const bf16_t* __restrict__ Kp, const bf16_t* __restrict__ Vt, int q0, int nkeys,
;                   bf16_t* __restrict__ mix, int colbase, int b, char* smem) {
;     ...
;   const int nt = nkeys >> 6;
;   A_LOAD(p, 0)
;   A_LOAD(q, 64)
;   A_WRITE(p, 0)
;   __syncthreads();
;   if (nt > 2) A_LOAD(p, 128)
;   for (int kt = 0; kt < nt; kt += 2) {
;     A_TILE(0)
;     A_WRITE(q, 1)
;     __syncthreads();
;     if (kt + 3 < nt) A_LOAD(q, (kt + 3) << 6)
;     A_TILE(1)
;     if (kt + 2 < nt) A_WRITE(p, 0)
;     __syncthreads();
;     if (kt + 4 < nt) A_LOAD(p, (kt + 4) << 6)
;   }
;     ...
;   l = xhalf_sum(l);
;   const float inv = 1.0f / l;
;   const int kp = q0 + wave * 32 + r;
;   bf16_t* orow = mix + (size_t)row_of(b, kp) * D + colbase;
; #pragma unroll
;   for (int g = 0; g < 4; ++g) {
;     uint2 w0, w1;
;     w0.x = pack2(o0[4 * g] * inv, o0[4 * g + 1] * inv); w0.y = pack2(o0[4 * g + 2] * inv, o0[4 * g + 3] * inv);
;     w1.x = pack2(o1[4 * g] * inv, o1[4 * g + 1] * inv); w1.y = pack2(o1[4 * g + 2] * inv, o1[4 * g + 3] * inv);
;     *(uint2*)(orow + 8 * g + 4 * h) = w0;
;     *(uint2*)(orow + 32 + 8 * g + 4 * h) = w1;
;   }
.Lat_nors_7:
	s_waitcnt lgkmcnt(3)
	v_mfma_f32_32x32x16_bf16 v[48:63], v[156:159], v[116:119], v[48:63]
	ds_read_b128 v[156:159], v238 offset:4704
	v_exp_f32_e32 v64, v64
	v_exp_f32_e32 v65, v65
	v_exp_f32_e32 v66, v66
	v_exp_f32_e32 v67, v67
	v_exp_f32_e32 v68, v68
	v_exp_f32_e32 v69, v69
	s_waitcnt lgkmcnt(3)
	v_mfma_f32_32x32x16_bf16 v[32:47], v[144:147], v[120:123], v[32:47]
	v_exp_f32_e32 v70, v70
	v_exp_f32_e32 v71, v71
	v_exp_f32_e32 v72, v72
	v_exp_f32_e32 v73, v73
	v_exp_f32_e32 v74, v74
	v_exp_f32_e32 v75, v75
	s_waitcnt lgkmcnt(2)
	v_mfma_f32_32x32x16_bf16 v[48:63], v[148:151], v[120:123], v[48:63]
	v_exp_f32_e32 v76, v76
	v_exp_f32_e32 v77, v77
	v_exp_f32_e32 v78, v78
	v_exp_f32_e32 v79, v79
	v_exp_f32_e32 v80, v80
	v_exp_f32_e32 v81, v81
	s_waitcnt lgkmcnt(1)
	v_mfma_f32_32x32x16_bf16 v[32:47], v[152:155], v[124:127], v[32:47]
	v_exp_f32_e32 v82, v82
	v_exp_f32_e32 v83, v83
	v_exp_f32_e32 v84, v84
	v_exp_f32_e32 v85, v85
	v_exp_f32_e32 v86, v86
	v_exp_f32_e32 v87, v87
	s_waitcnt lgkmcnt(0)
	v_mfma_f32_32x32x16_bf16 v[48:63], v[156:159], v[124:127], v[48:63]
	v_exp_f32_e32 v88, v88
	v_exp_f32_e32 v89, v89
	v_exp_f32_e32 v90, v90
	v_exp_f32_e32 v91, v91
	v_exp_f32_e32 v92, v92
	v_exp_f32_e32 v93, v93
	v_exp_f32_e32 v94, v94
	v_exp_f32_e32 v95, v95
	v_add_u32_e32 v223, 0x6a00, v239
	v_add_u32_e32 v224, 0x6a00, v240
	ds_read2_b64 v[144:147], v223 offset0:0 offset1:2
	ds_read2_b64 v[148:151], v224 offset0:0 offset1:2
	ds_read2_b64 v[152:155], v223 offset0:4 offset1:6
	ds_read2_b64 v[156:159], v224 offset0:4 offset1:6
	v_cvt_pk_bf16_f32 v96, v64, v65
	v_cvt_pk_bf16_f32 v97, v66, v67
	v_cvt_pk_bf16_f32 v98, v68, v69
	v_cvt_pk_bf16_f32 v99, v70, v71
	v_add_f32_e32 v231, v64, v68
	v_add_f32_e32 v232, v65, v69
	v_add_f32_e32 v233, v66, v70
	v_add_f32_e32 v237, v67, v71
	s_waitcnt lgkmcnt(3)
	v_mfma_f32_32x32x16_bf16 v[0:15], v[144:147], v[96:99], v[0:15]
	ds_read2_b64 v[144:147], v223 offset0:8 offset1:10
	s_waitcnt lgkmcnt(3)
	v_mfma_f32_32x32x16_bf16 v[16:31], v[148:151], v[96:99], v[16:31]
	ds_read2_b64 v[148:151], v224 offset0:8 offset1:10
	v_cvt_pk_bf16_f32 v100, v72, v73
	v_cvt_pk_bf16_f32 v101, v74, v75
	v_cvt_pk_bf16_f32 v102, v76, v77
	v_cvt_pk_bf16_f32 v103, v78, v79
	v_add_f32_e32 v231, v231, v72
	v_add_f32_e32 v232, v232, v73
	v_add_f32_e32 v233, v233, v74
	v_add_f32_e32 v237, v237, v75
	v_add_f32_e32 v231, v231, v76
	v_add_f32_e32 v232, v232, v77
	v_add_f32_e32 v233, v233, v78
	v_add_f32_e32 v237, v237, v79
	s_waitcnt lgkmcnt(3)
	v_mfma_f32_32x32x16_bf16 v[0:15], v[152:155], v[100:103], v[0:15]
	ds_read2_b64 v[152:155], v223 offset0:12 offset1:14
	s_waitcnt lgkmcnt(3)
	v_mfma_f32_32x32x16_bf16 v[16:31], v[156:159], v[100:103], v[16:31]
	ds_read2_b64 v[156:159], v224 offset0:12 offset1:14
	v_cvt_pk_bf16_f32 v104, v80, v81
	v_cvt_pk_bf16_f32 v105, v82, v83
	v_cvt_pk_bf16_f32 v106, v84, v85
	v_cvt_pk_bf16_f32 v107, v86, v87
	v_add_f32_e32 v231, v231, v80
	v_add_f32_e32 v232, v232, v81
	v_add_f32_e32 v233, v233, v82
	v_add_f32_e32 v237, v237, v83
	v_add_f32_e32 v231, v231, v84
	v_add_f32_e32 v232, v232, v85
	v_add_f32_e32 v233, v233, v86
	v_add_f32_e32 v237, v237, v87
	s_waitcnt lgkmcnt(3)
	v_mfma_f32_32x32x16_bf16 v[0:15], v[144:147], v[104:107], v[0:15]
	s_waitcnt lgkmcnt(2)
	v_mfma_f32_32x32x16_bf16 v[16:31], v[148:151], v[104:107], v[16:31]
	v_cvt_pk_bf16_f32 v108, v88, v89
	v_cvt_pk_bf16_f32 v109, v90, v91
	v_cvt_pk_bf16_f32 v110, v92, v93
	v_cvt_pk_bf16_f32 v111, v94, v95
	v_add_f32_e32 v231, v231, v88
	v_add_f32_e32 v232, v232, v89
	v_add_f32_e32 v233, v233, v90
	v_add_f32_e32 v237, v237, v91
	v_add_f32_e32 v231, v231, v92
	v_add_f32_e32 v232, v232, v93
	v_add_f32_e32 v233, v233, v94
	v_add_f32_e32 v237, v237, v95
	s_waitcnt lgkmcnt(1)
	v_mfma_f32_32x32x16_bf16 v[0:15], v[152:155], v[108:111], v[0:15]
	s_waitcnt lgkmcnt(0)
	v_mfma_f32_32x32x16_bf16 v[16:31], v[156:159], v[108:111], v[16:31]
	v_add_f32_e32 v231, v231, v232
	v_add_f32_e32 v233, v233, v237
	v_add_f32_e32 v231, v231, v233
	v_add_f32_e32 v221, v221, v231
	s_add_u32 s68, s68, 1
	s_waitcnt lgkmcnt(0)
	s_barrier
	s_cmp_lt_u32 s68, 68
	s_cbranch_scc1 .Lat_loop_g
	s_nop 7
	v_mov_b32_e32 v223, v221
	s_nop 1
	v_permlane32_swap_b32_e32 v221, v223
	v_add_f32_e32 v221, v221, v223
	v_rcp_f32_e32 v224, v221
	v_add_u32_e32 v226, 0x220000, v252
	s_nop 0
	v_mul_f32_e32 v96, v0, v224
	v_mul_f32_e32 v97, v1, v224
	v_mul_f32_e32 v98, v2, v224
	v_mul_f32_e32 v99, v3, v224
	v_cvt_pk_bf16_f32 v144, v96, v97
	v_cvt_pk_bf16_f32 v145, v98, v99
	global_store_dwordx2 v252, v[144:145], s[72:73] offset:0
	v_mul_f32_e32 v96, v16, v224
	v_mul_f32_e32 v97, v17, v224
	v_mul_f32_e32 v98, v18, v224
	v_mul_f32_e32 v99, v19, v224
	v_cvt_pk_bf16_f32 v146, v96, v97
	v_cvt_pk_bf16_f32 v147, v98, v99
	global_store_dwordx2 v226, v[146:147], s[72:73] offset:0
	v_mul_f32_e32 v96, v4, v224
	v_mul_f32_e32 v97, v5, v224
	v_mul_f32_e32 v98, v6, v224
	v_mul_f32_e32 v99, v7, v224
	v_cvt_pk_bf16_f32 v148, v96, v97
	v_cvt_pk_bf16_f32 v149, v98, v99
	global_store_dwordx2 v252, v[148:149], s[72:73] offset:16
	v_mul_f32_e32 v96, v20, v224
	v_mul_f32_e32 v97, v21, v224
	v_mul_f32_e32 v98, v22, v224
	v_mul_f32_e32 v99, v23, v224
	v_cvt_pk_bf16_f32 v150, v96, v97
	v_cvt_pk_bf16_f32 v151, v98, v99
	global_store_dwordx2 v226, v[150:151], s[72:73] offset:16
	v_mul_f32_e32 v96, v8, v224
	v_mul_f32_e32 v97, v9, v224
	v_mul_f32_e32 v98, v10, v224
	v_mul_f32_e32 v99, v11, v224
	v_cvt_pk_bf16_f32 v152, v96, v97
	v_cvt_pk_bf16_f32 v153, v98, v99
	global_store_dwordx2 v252, v[152:153], s[72:73] offset:32
	v_mul_f32_e32 v96, v24, v224
	v_mul_f32_e32 v97, v25, v224
	v_mul_f32_e32 v98, v26, v224
	v_mul_f32_e32 v99, v27, v224
	v_cvt_pk_bf16_f32 v154, v96, v97
	v_cvt_pk_bf16_f32 v155, v98, v99
	global_store_dwordx2 v226, v[154:155], s[72:73] offset:32
	v_mul_f32_e32 v96, v12, v224
	v_mul_f32_e32 v97, v13, v224
	v_mul_f32_e32 v98, v14, v224
	v_mul_f32_e32 v99, v15, v224
	v_cvt_pk_bf16_f32 v156, v96, v97
	v_cvt_pk_bf16_f32 v157, v98, v99
	global_store_dwordx2 v252, v[156:157], s[72:73] offset:48
	v_mul_f32_e32 v96, v28, v224
	v_mul_f32_e32 v97, v29, v224
	v_mul_f32_e32 v98, v30, v224
	v_mul_f32_e32 v99, v31, v224
	v_cvt_pk_bf16_f32 v158, v96, v97
	v_cvt_pk_bf16_f32 v159, v98, v99
	global_store_dwordx2 v226, v[158:159], s[72:73] offset:48
	s_branch .Lat_tyj_3
; template <int DQK>
; DI void attn_item(const bf16_t* __restrict__ Q, const bf16_t* __restrict__ Kp, const bf16_t* __restrict__ Vt, int q0, int nkeys,
;                   bf16_t* __restrict__ mix, int colbase, int b, char* smem) {
;     ...
;   bf16x8 qf[NSTEP];
;   {
;     const bf16_t* qr = Q + (size_t)(q0 + wave * 32 + r) * DQK + 8 * h;
; #pragma unroll
;     for (int s = 0; s < NSTEP; ++s) qf[s] = *(const bf16x8*)(qr + 16 * s);
;   }
;   const int kid0 = tid, kid1 = tid + 256, kid2 = tid + 512;
;   const int kgo0 = (kid0 / KCH) * DQK + (kid0 % KCH) * 8, kgo1 = (kid1 / KCH) * DQK + (kid1 % KCH) * 8, kgo2 = (kid2 / KCH) * DQK + (kid2 % KCH) * 8;
;   const int kso0 = (kid0 / KCH) * KROW + (kid0 % KCH) * 8, kso1 = (kid1 / KCH) * KROW + (kid1 % KCH) * 8, kso2 = (kid2 / KCH) * KROW + (kid2 % KCH) * 8;
;   const int vrow0 = tid >> 3, vcc = (tid & 7) * 8;
;   const bf16_t* Vg0 = Vt + (size_t)vrow0 * NKEY + vcc;
;   const bf16_t* Vg1 = Vt + (size_t)(vrow0 + 32) * NKEY + vcc;
;   const int vso0 = vrow0 * VROW + vcc, vso1 = (vrow0 + 32) * VROW + vcc;
;   uint4 pk0, pk1, pk2, pv0, pv1, qk0, qk1, qk2, qv0, qv1;
;   pk2 = make_uint4(0, 0, 0, 0); qk2 = pk2;
;     ...
;   f32x16 o0, o1;
; #pragma unroll
;   for (int i = 0; i < 16; ++i) { o0[i] = 0.f; o1[i] = 0.f; }
;   float m = -1e30f, l = 0.f;
; DI void attn_dispatch(const Params& p, int type, int b, int hd, int qb, char* smem) {
;     ...
;   } else {
;     const bf16_t* Q = (const bf16_t*)(p.ws + OFF_QM) + (size_t)(b * 6 + hd) * NKEY * 96;
;     const bf16_t* K = (const bf16_t*)(p.ws + OFF_KM) + (size_t)(b * 6 + hd) * NKEY * 96;
;     const bf16_t* V = (const bf16_t*)(p.ws + OFF_VMT) + (size_t)(b * 6 + hd) * 64 * NKEY;
;     attn_item<96>(Q, K, V, qb * 128, nkeys, MIX, 640 + hd * 64, b, smem);
.Lat_mla_2:
	s_mul_i32 s11, s54, 6
	s_add_u32 s11, s11, s55
	s_mul_i32 s28, s11, 0xcc000
	s_add_u32 s28, s28, 0xaa00000
	s_add_u32 s58, s24, s28
	s_addc_u32 s59, s25, 0
	s_mul_i32 s28, s11, 0xcc000
	s_add_u32 s28, s28, 0xd040000
	s_add_u32 s60, s24, s28
	s_addc_u32 s61, s25, 0
	s_mul_i32 s28, s11, 0x88000
	s_add_u32 s28, s28, 0xf680000
	s_add_u32 s62, s24, s28
	s_addc_u32 s63, s25, 0
	s_lshl_b32 s28, s55, 1
	s_add_u32 s28, s28, 20
	s_mul_i32 s28, s28, 0x220000
	v_add_u32_e32 v252, s28, v252
	s_lshl_b32 s28, s57, 5
	s_add_u32 s28, s28, s56
	v_add_u32_e32 v251, s28, v253
	s_movk_i32 s29, 192
	v_mul_lo_u32 v251, v251, s29
	v_lshl_add_u32 v251, v140, 4, v251
	s_movk_i32 s29, 208
	v_mul_lo_u32 v238, v253, s29
	v_lshl_add_u32 v238, v140, 4, v238
	s_movk_i32 s29, 136
	v_mul_lo_u32 v239, v253, s29
	v_lshl_add_u32 v239, v140, 3, v239
	v_add_u32_e32 v240, 0x1100, v239
	v_mov_b32_e32 v225, v143
	s_mov_b32 s29, 0xaaab
	v_mul_u32_u24_e32 v226, 0xaaab, v225
	v_lshrrev_b32_e32 v226, 19, v226
	v_mul_u32_u24_e32 v227, 12, v226
	v_sub_u32_e32 v227, v225, v227
	s_movk_i32 s29, 192
	v_mul_lo_u32 v246, v226, s29
	v_lshl_add_u32 v246, v227, 4, v246
	s_movk_i32 s29, 208
	v_mul_lo_u32 v241, v226, s29
	v_lshl_add_u32 v241, v227, 4, v241
	v_add_u32_e32 v225, 256, v143
	s_mov_b32 s29, 0xaaab
	v_mul_u32_u24_e32 v226, 0xaaab, v225
	v_lshrrev_b32_e32 v226, 19, v226
	v_mul_u32_u24_e32 v227, 12, v226
	v_sub_u32_e32 v227, v225, v227
	s_movk_i32 s29, 192
	v_mul_lo_u32 v247, v226, s29
	v_lshl_add_u32 v247, v227, 4, v247
	s_movk_i32 s29, 208
	v_mul_lo_u32 v242, v226, s29
	v_lshl_add_u32 v242, v227, 4, v242
	v_add_u32_e32 v225, 512, v143
	s_mov_b32 s29, 0xaaab
	v_mul_u32_u24_e32 v226, 0xaaab, v225
	v_lshrrev_b32_e32 v226, 19, v226
	v_mul_u32_u24_e32 v227, 12, v226
	v_sub_u32_e32 v227, v225, v227
	s_movk_i32 s29, 192
	v_mul_lo_u32 v248, v226, s29
	v_lshl_add_u32 v248, v227, 4, v248
	s_movk_i32 s29, 208
	v_mul_lo_u32 v243, v226, s29
	v_lshl_add_u32 v243, v227, 4, v243
	v_lshrrev_b32_e32 v226, 3, v143
	v_and_b32_e32 v227, 7, v143
	s_movk_i32 s29, 8704
	v_mul_lo_u32 v249, v226, s29
	v_lshl_add_u32 v249, v227, 4, v249
	v_add_u32_e32 v250, 0x44000, v249
	s_movk_i32 s29, 136
	v_mul_lo_u32 v244, v226, s29
	v_lshl_add_u32 v244, v227, 4, v244
	v_add_u32_e32 v245, 0x1100, v244
	s_barrier
	global_load_dwordx4 v[112:115], v251, s[58:59] offset:0
	global_load_dwordx4 v[116:119], v251, s[58:59] offset:32
	global_load_dwordx4 v[120:123], v251, s[58:59] offset:64
	global_load_dwordx4 v[124:127], v251, s[58:59] offset:96
	global_load_dwordx4 v[128:131], v251, s[58:59] offset:128
	global_load_dwordx4 v[132:135], v251, s[58:59] offset:160
	s_mov_b32 s1, 0
	s_min_u32 s0, s1, 67
	s_mul_i32 s0, s0, 0x3000
	s_add_u32 s64, s60, s0
	s_addc_u32 s65, s61, 0
	s_min_u32 s0, s1, 67
	s_lshl_b32 s0, s0, 7
	s_add_u32 s66, s62, s0
	s_addc_u32 s67, s63, 0
	global_load_dwordx4 v[176:179], v246, s[64:65]
	global_load_dwordx4 v[180:183], v247, s[64:65]
	global_load_dwordx4 v[184:187], v248, s[64:65]
	global_load_dwordx4 v[212:215], v249, s[66:67]
	global_load_dwordx4 v[216:219], v250, s[66:67]
	s_waitcnt vmcnt(0)
	ds_write_b128 v241, v[176:179] offset:0
	ds_write_b128 v242, v[180:183] offset:0
	ds_write_b128 v243, v[184:187] offset:0
	ds_write_b64 v244, v[212:213] offset:26624
	ds_write_b64 v244, v[214:215] offset:26632
	ds_write_b64 v245, v[216:217] offset:26624
	ds_write_b64 v245, v[218:219] offset:26632
	s_mov_b32 s1, 1
	s_min_u32 s0, s1, 67
	s_mul_i32 s0, s0, 0x3000
	s_add_u32 s64, s60, s0
	s_addc_u32 s65, s61, 0
	s_min_u32 s0, s1, 67
	s_lshl_b32 s0, s0, 7
	s_add_u32 s66, s62, s0
	s_addc_u32 s67, s63, 0
	global_load_dwordx4 v[176:179], v246, s[64:65]
	global_load_dwordx4 v[180:183], v247, s[64:65]
	global_load_dwordx4 v[184:187], v248, s[64:65]
	s_waitcnt vmcnt(0)
	ds_write_b128 v241, v[176:179] offset:13312
	ds_write_b128 v242, v[180:183] offset:13312
	ds_write_b128 v243, v[184:187] offset:13312
	s_mov_b32 s1, 2
	s_mov_b32 s10, 1
	s_min_u32 s0, s1, 67
	s_mul_i32 s0, s0, 0x3000
	s_add_u32 s64, s60, s0
	s_addc_u32 s65, s61, 0
	s_min_u32 s0, s10, 67
	s_lshl_b32 s0, s0, 7
	s_add_u32 s66, s62, s0
	s_addc_u32 s67, s63, 0
	global_load_dwordx4 v[176:179], v246, s[64:65]
	global_load_dwordx4 v[180:183], v247, s[64:65]
	global_load_dwordx4 v[184:187], v248, s[64:65]
	global_load_dwordx4 v[212:215], v249, s[66:67]
	global_load_dwordx4 v[216:219], v250, s[66:67]
	v_mov_b32_e32 v0, 0
	v_mov_b32_e32 v1, 0
	v_mov_b32_e32 v2, 0
	v_mov_b32_e32 v3, 0
	v_mov_b32_e32 v4, 0
	v_mov_b32_e32 v5, 0
	v_mov_b32_e32 v6, 0
	v_mov_b32_e32 v7, 0
	v_mov_b32_e32 v8, 0
	v_mov_b32_e32 v9, 0
	v_mov_b32_e32 v10, 0
	v_mov_b32_e32 v11, 0
	v_mov_b32_e32 v12, 0
	v_mov_b32_e32 v13, 0
	v_mov_b32_e32 v14, 0
	v_mov_b32_e32 v15, 0
	v_mov_b32_e32 v16, 0
	v_mov_b32_e32 v17, 0
	v_mov_b32_e32 v18, 0
	v_mov_b32_e32 v19, 0
	v_mov_b32_e32 v20, 0
	v_mov_b32_e32 v21, 0
	v_mov_b32_e32 v22, 0
	v_mov_b32_e32 v23, 0
	v_mov_b32_e32 v24, 0
	v_mov_b32_e32 v25, 0
	v_mov_b32_e32 v26, 0
	v_mov_b32_e32 v27, 0
	v_mov_b32_e32 v28, 0
	v_mov_b32_e32 v29, 0
	v_mov_b32_e32 v30, 0
	v_mov_b32_e32 v31, 0
	v_mov_b32_e32 v221, 0
	s_waitcnt lgkmcnt(0)
	s_barrier
	ds_read_b128 v[144:147], v238 offset:0
	ds_read_b128 v[148:151], v238 offset:6656
	ds_read_b128 v[152:155], v238 offset:32
	ds_read_b128 v[156:159], v238 offset:6688
	s_waitcnt lgkmcnt(3)
	v_mfma_f32_32x32x16_bf16 v[32:47], v[144:147], v[112:115], 0
	ds_read_b128 v[144:147], v238 offset:64
	s_waitcnt lgkmcnt(3)
	v_mfma_f32_32x32x16_bf16 v[48:63], v[148:151], v[112:115], 0
	ds_read_b128 v[148:151], v238 offset:6720
	s_waitcnt lgkmcnt(3)
	v_mfma_f32_32x32x16_bf16 v[32:47], v[152:155], v[116:119], v[32:47]
	ds_read_b128 v[152:155], v238 offset:96
	s_waitcnt lgkmcnt(3)
	v_mfma_f32_32x32x16_bf16 v[48:63], v[156:159], v[116:119], v[48:63]
	ds_read_b128 v[156:159], v238 offset:6752
	s_waitcnt lgkmcnt(3)
	v_mfma_f32_32x32x16_bf16 v[32:47], v[144:147], v[120:123], v[32:47]
	ds_read_b128 v[144:147], v238 offset:128
	s_waitcnt lgkmcnt(3)
	v_mfma_f32_32x32x16_bf16 v[48:63], v[148:151], v[120:123], v[48:63]
	ds_read_b128 v[148:151], v238 offset:6784
	s_waitcnt lgkmcnt(3)
	v_mfma_f32_32x32x16_bf16 v[32:47], v[152:155], v[124:127], v[32:47]
	ds_read_b128 v[152:155], v238 offset:160
	s_waitcnt lgkmcnt(3)
	v_mfma_f32_32x32x16_bf16 v[48:63], v[156:159], v[124:127], v[48:63]
	ds_read_b128 v[156:159], v238 offset:6816
	s_waitcnt lgkmcnt(3)
	v_mfma_f32_32x32x16_bf16 v[32:47], v[144:147], v[128:131], v[32:47]
	s_waitcnt lgkmcnt(2)
	v_mfma_f32_32x32x16_bf16 v[48:63], v[148:151], v[128:131], v[48:63]
	s_waitcnt lgkmcnt(1)
	v_mfma_f32_32x32x16_bf16 v[32:47], v[152:155], v[132:135], v[32:47]
	s_waitcnt lgkmcnt(0)
	v_mfma_f32_32x32x16_bf16 v[48:63], v[156:159], v[132:135], v[48:63]
	s_waitcnt lgkmcnt(0)
	s_barrier
	s_nop 7
	s_nop 3
	v_max3_f32 v223, v32, v33, v34
	v_max3_f32 v224, v40, v41, v42
	v_max3_f32 v225, v48, v49, v50
	v_max3_f32 v226, v56, v57, v58
	v_max3_f32 v223, v223, v35, v36
	v_max3_f32 v224, v224, v43, v44
	v_max3_f32 v225, v225, v51, v52
	v_max3_f32 v226, v226, v59, v60
	v_max3_f32 v223, v223, v37, v38
	v_max3_f32 v224, v224, v45, v46
	v_max3_f32 v225, v225, v53, v54
	v_max3_f32 v226, v226, v61, v62
	v_max_f32_e32 v223, v223, v39
	v_max_f32_e32 v224, v224, v47
	v_max_f32_e32 v225, v225, v55
	v_max_f32_e32 v226, v226, v63
	v_max3_f32 v222, v223, v224, v225
	v_max_f32_e32 v222, v222, v226
	v_mov_b32_e32 v227, v222
	s_nop 1
	v_permlane32_swap_b32_e32 v222, v227
	v_max_f32_e32 v222, v222, v227
	v_sub_f32_e32 v32, v32, v222
	v_sub_f32_e32 v33, v33, v222
	v_sub_f32_e32 v34, v34, v222
	v_sub_f32_e32 v35, v35, v222
	v_sub_f32_e32 v36, v36, v222
	v_sub_f32_e32 v37, v37, v222
	v_sub_f32_e32 v38, v38, v222
	v_sub_f32_e32 v39, v39, v222
	v_sub_f32_e32 v40, v40, v222
	v_sub_f32_e32 v41, v41, v222
	v_sub_f32_e32 v42, v42, v222
	v_sub_f32_e32 v43, v43, v222
	v_sub_f32_e32 v44, v44, v222
	v_sub_f32_e32 v45, v45, v222
	v_sub_f32_e32 v46, v46, v222
	v_sub_f32_e32 v47, v47, v222
	v_sub_f32_e32 v48, v48, v222
	v_sub_f32_e32 v49, v49, v222
	v_sub_f32_e32 v50, v50, v222
	v_sub_f32_e32 v51, v51, v222
	v_sub_f32_e32 v52, v52, v222
	v_sub_f32_e32 v53, v53, v222
	v_sub_f32_e32 v54, v54, v222
	v_sub_f32_e32 v55, v55, v222
	v_sub_f32_e32 v56, v56, v222
	v_sub_f32_e32 v57, v57, v222
	v_sub_f32_e32 v58, v58, v222
	v_sub_f32_e32 v59, v59, v222
	v_sub_f32_e32 v60, v60, v222
	v_sub_f32_e32 v61, v61, v222
	v_sub_f32_e32 v62, v62, v222
	v_sub_f32_e32 v63, v63, v222
	v_sub_f32_e32 v160, 0, v222
	v_sub_f32_e32 v161, 0, v222
	v_sub_f32_e32 v162, 0, v222
	v_sub_f32_e32 v163, 0, v222
	v_sub_f32_e32 v164, 0, v222
	v_sub_f32_e32 v165, 0, v222
	v_sub_f32_e32 v166, 0, v222
	v_sub_f32_e32 v167, 0, v222
	v_sub_f32_e32 v168, 0, v222
	v_sub_f32_e32 v169, 0, v222
	v_sub_f32_e32 v170, 0, v222
	v_sub_f32_e32 v171, 0, v222
	v_sub_f32_e32 v172, 0, v222
	v_sub_f32_e32 v173, 0, v222
	v_sub_f32_e32 v174, 0, v222
	v_sub_f32_e32 v175, 0, v222
	s_mov_b32 s69, 0
	s_mov_b32 s68, 0

; DI unsigned pack2(float lo, float hi) { f32x2_t v = {lo, hi}; bf16x2_t r = __builtin_convertvector(v, bf16x2_t); return __builtin_bit_cast(unsigned, r); }
; DI float xhalf_sum(float x) { auto r = __builtin_amdgcn_permlane32_swap(__float_as_uint(x), __float_as_uint(x), false, false); return __uint_as_float(r[0]) + __uint_as_float(r[1]); }
; template <int DQK>
; DI void attn_item(const bf16_t* __restrict__ Q, const bf16_t* __restrict__ Kp, const bf16_t* __restrict__ Vt, int q0, int nkeys,
;                   bf16_t* __restrict__ mix, int colbase, int b, char* smem) {
;     ...
;   const int nt = nkeys >> 6;
;   A_LOAD(p, 0)
;   A_LOAD(q, 64)
;   A_WRITE(p, 0)
;   __syncthreads();
;   if (nt > 2) A_LOAD(p, 128)
;   for (int kt = 0; kt < nt; kt += 2) {
;     A_TILE(0)
;     A_WRITE(q, 1)
;     __syncthreads();
;     if (kt + 3 < nt) A_LOAD(q, (kt + 3) << 6)
;     A_TILE(1)
;     if (kt + 2 < nt) A_WRITE(p, 0)
;     __syncthreads();
;     if (kt + 4 < nt) A_LOAD(p, (kt + 4) << 6)
;   }
;     ...
;   l = xhalf_sum(l);
;   const float inv = 1.0f / l;
;   const int kp = q0 + wave * 32 + r;
;   bf16_t* orow = mix + (size_t)row_of(b, kp) * D + colbase;
; #pragma unroll
;   for (int g = 0; g < 4; ++g) {
;     uint2 w0, w1;
;     w0.x = pack2(o0[4 * g] * inv, o0[4 * g + 1] * inv); w0.y = pack2(o0[4 * g + 2] * inv, o0[4 * g + 3] * inv);
;     w1.x = pack2(o1[4 * g] * inv, o1[4 * g + 1] * inv); w1.y = pack2(o1[4 * g + 2] * inv, o1[4 * g + 3] * inv);
;     *(uint2*)(orow + 8 * g + 4 * h) = w0;
;     *(uint2*)(orow + 32 + 8 * g + 4 * h) = w1;
;   }
.Lat_nors_11:
	s_waitcnt lgkmcnt(3)
	v_mfma_f32_32x32x16_bf16 v[48:63], v[148:151], v[120:123], v[48:63]
	ds_read_b128 v[148:151], v238 offset:6784
	v_exp_f32_e32 v64, v64
	v_exp_f32_e32 v65, v65
	v_exp_f32_e32 v66, v66
	v_exp_f32_e32 v67, v67
	s_waitcnt lgkmcnt(3)
	v_mfma_f32_32x32x16_bf16 v[32:47], v[152:155], v[124:127], v[32:47]
	ds_read_b128 v[152:155], v238 offset:160
	v_exp_f32_e32 v68, v68
	v_exp_f32_e32 v69, v69
	v_exp_f32_e32 v70, v70
	v_exp_f32_e32 v71, v71
	s_waitcnt lgkmcnt(3)
	v_mfma_f32_32x32x16_bf16 v[48:63], v[156:159], v[124:127], v[48:63]
	ds_read_b128 v[156:159], v238 offset:6816
	v_exp_f32_e32 v72, v72
	v_exp_f32_e32 v73, v73
	v_exp_f32_e32 v74, v74
	v_exp_f32_e32 v75, v75
	s_waitcnt lgkmcnt(3)
	v_mfma_f32_32x32x16_bf16 v[32:47], v[144:147], v[128:131], v[32:47]
	v_exp_f32_e32 v76, v76
	v_exp_f32_e32 v77, v77
	v_exp_f32_e32 v78, v78
	v_exp_f32_e32 v79, v79
	s_waitcnt lgkmcnt(2)
	v_mfma_f32_32x32x16_bf16 v[48:63], v[148:151], v[128:131], v[48:63]
	v_exp_f32_e32 v80, v80
	v_exp_f32_e32 v81, v81
	v_exp_f32_e32 v82, v82
	v_exp_f32_e32 v83, v83
	s_waitcnt lgkmcnt(1)
	v_mfma_f32_32x32x16_bf16 v[32:47], v[152:155], v[132:135], v[32:47]
	v_exp_f32_e32 v84, v84
	v_exp_f32_e32 v85, v85
	v_exp_f32_e32 v86, v86
	v_exp_f32_e32 v87, v87
	s_waitcnt lgkmcnt(0)
	v_mfma_f32_32x32x16_bf16 v[48:63], v[156:159], v[132:135], v[48:63]
	v_exp_f32_e32 v88, v88
	v_exp_f32_e32 v89, v89
	v_exp_f32_e32 v90, v90
	v_exp_f32_e32 v91, v91
	v_exp_f32_e32 v92, v92
	v_exp_f32_e32 v93, v93
	v_exp_f32_e32 v94, v94
	v_exp_f32_e32 v95, v95
	v_add_u32_e32 v223, 0x8a00, v239
	v_add_u32_e32 v224, 0x8a00, v240
	ds_read2_b64 v[144:147], v223 offset0:0 offset1:2
	ds_read2_b64 v[148:151], v224 offset0:0 offset1:2
	ds_read2_b64 v[152:155], v223 offset0:4 offset1:6
	ds_read2_b64 v[156:159], v224 offset0:4 offset1:6
	v_cvt_pk_bf16_f32 v96, v64, v65
	v_cvt_pk_bf16_f32 v97, v66, v67
	v_cvt_pk_bf16_f32 v98, v68, v69
	v_cvt_pk_bf16_f32 v99, v70, v71
	v_add_f32_e32 v231, v64, v68
	v_add_f32_e32 v232, v65, v69
	v_add_f32_e32 v233, v66, v70
	v_add_f32_e32 v237, v67, v71
	s_waitcnt lgkmcnt(3)
	v_mfma_f32_32x32x16_bf16 v[0:15], v[144:147], v[96:99], v[0:15]
	ds_read2_b64 v[144:147], v223 offset0:8 offset1:10
	s_waitcnt lgkmcnt(3)
	v_mfma_f32_32x32x16_bf16 v[16:31], v[148:151], v[96:99], v[16:31]
	ds_read2_b64 v[148:151], v224 offset0:8 offset1:10
	v_cvt_pk_bf16_f32 v100, v72, v73
	v_cvt_pk_bf16_f32 v101, v74, v75
	v_cvt_pk_bf16_f32 v102, v76, v77
	v_cvt_pk_bf16_f32 v103, v78, v79
	v_add_f32_e32 v231, v231, v72
	v_add_f32_e32 v232, v232, v73
	v_add_f32_e32 v233, v233, v74
	v_add_f32_e32 v237, v237, v75
	v_add_f32_e32 v231, v231, v76
	v_add_f32_e32 v232, v232, v77
	v_add_f32_e32 v233, v233, v78
	v_add_f32_e32 v237, v237, v79
	s_waitcnt lgkmcnt(3)
	v_mfma_f32_32x32x16_bf16 v[0:15], v[152:155], v[100:103], v[0:15]
	ds_read2_b64 v[152:155], v223 offset0:12 offset1:14
	s_waitcnt lgkmcnt(3)
	v_mfma_f32_32x32x16_bf16 v[16:31], v[156:159], v[100:103], v[16:31]
	ds_read2_b64 v[156:159], v224 offset0:12 offset1:14
	v_cvt_pk_bf16_f32 v104, v80, v81
	v_cvt_pk_bf16_f32 v105, v82, v83
	v_cvt_pk_bf16_f32 v106, v84, v85
	v_cvt_pk_bf16_f32 v107, v86, v87
	v_add_f32_e32 v231, v231, v80
	v_add_f32_e32 v232, v232, v81
	v_add_f32_e32 v233, v233, v82
	v_add_f32_e32 v237, v237, v83
	v_add_f32_e32 v231, v231, v84
	v_add_f32_e32 v232, v232, v85
	v_add_f32_e32 v233, v233, v86
	v_add_f32_e32 v237, v237, v87
	s_waitcnt lgkmcnt(3)
	v_mfma_f32_32x32x16_bf16 v[0:15], v[144:147], v[104:107], v[0:15]
	s_waitcnt lgkmcnt(2)
	v_mfma_f32_32x32x16_bf16 v[16:31], v[148:151], v[104:107], v[16:31]
	v_cvt_pk_bf16_f32 v108, v88, v89
	v_cvt_pk_bf16_f32 v109, v90, v91
	v_cvt_pk_bf16_f32 v110, v92, v93
	v_cvt_pk_bf16_f32 v111, v94, v95
	v_add_f32_e32 v231, v231, v88
	v_add_f32_e32 v232, v232, v89
	v_add_f32_e32 v233, v233, v90
	v_add_f32_e32 v237, v237, v91
	v_add_f32_e32 v231, v231, v92
	v_add_f32_e32 v232, v232, v93
	v_add_f32_e32 v233, v233, v94
	v_add_f32_e32 v237, v237, v95
	s_waitcnt lgkmcnt(1)
	v_mfma_f32_32x32x16_bf16 v[0:15], v[152:155], v[108:111], v[0:15]
	s_waitcnt lgkmcnt(0)
	v_mfma_f32_32x32x16_bf16 v[16:31], v[156:159], v[108:111], v[16:31]
	v_add_f32_e32 v231, v231, v232
	v_add_f32_e32 v233, v233, v237
	v_add_f32_e32 v231, v231, v233
	v_add_f32_e32 v221, v221, v231
	s_add_u32 s68, s68, 1
	s_waitcnt lgkmcnt(0)
	s_barrier
	s_cmp_lt_u32 s68, 68
	s_cbranch_scc1 .Lat_loop_m
	s_nop 7
	v_mov_b32_e32 v223, v221
	s_nop 1
	v_permlane32_swap_b32_e32 v221, v223
	v_add_f32_e32 v221, v221, v223
	v_rcp_f32_e32 v224, v221
	v_add_u32_e32 v226, 0x220000, v252
	s_nop 0
	v_mul_f32_e32 v96, v0, v224
	v_mul_f32_e32 v97, v1, v224
	v_mul_f32_e32 v98, v2, v224
	v_mul_f32_e32 v99, v3, v224
	v_cvt_pk_bf16_f32 v144, v96, v97
	v_cvt_pk_bf16_f32 v145, v98, v99
	global_store_dwordx2 v252, v[144:145], s[72:73] offset:0
	v_mul_f32_e32 v96, v16, v224
	v_mul_f32_e32 v97, v17, v224
	v_mul_f32_e32 v98, v18, v224
	v_mul_f32_e32 v99, v19, v224
	v_cvt_pk_bf16_f32 v146, v96, v97
	v_cvt_pk_bf16_f32 v147, v98, v99
	global_store_dwordx2 v226, v[146:147], s[72:73] offset:0
	v_mul_f32_e32 v96, v4, v224
	v_mul_f32_e32 v97, v5, v224
	v_mul_f32_e32 v98, v6, v224
	v_mul_f32_e32 v99, v7, v224
	v_cvt_pk_bf16_f32 v148, v96, v97
	v_cvt_pk_bf16_f32 v149, v98, v99
	global_store_dwordx2 v252, v[148:149], s[72:73] offset:16
	v_mul_f32_e32 v96, v20, v224
	v_mul_f32_e32 v97, v21, v224
	v_mul_f32_e32 v98, v22, v224
	v_mul_f32_e32 v99, v23, v224
	v_cvt_pk_bf16_f32 v150, v96, v97
	v_cvt_pk_bf16_f32 v151, v98, v99
	global_store_dwordx2 v226, v[150:151], s[72:73] offset:16
	v_mul_f32_e32 v96, v8, v224
	v_mul_f32_e32 v97, v9, v224
	v_mul_f32_e32 v98, v10, v224
	v_mul_f32_e32 v99, v11, v224
	v_cvt_pk_bf16_f32 v152, v96, v97
	v_cvt_pk_bf16_f32 v153, v98, v99
	global_store_dwordx2 v252, v[152:153], s[72:73] offset:32
	v_mul_f32_e32 v96, v24, v224
	v_mul_f32_e32 v97, v25, v224
	v_mul_f32_e32 v98, v26, v224
	v_mul_f32_e32 v99, v27, v224
	v_cvt_pk_bf16_f32 v154, v96, v97
	v_cvt_pk_bf16_f32 v155, v98, v99
	global_store_dwordx2 v226, v[154:155], s[72:73] offset:32
	v_mul_f32_e32 v96, v12, v224
	v_mul_f32_e32 v97, v13, v224
	v_mul_f32_e32 v98, v14, v224
	v_mul_f32_e32 v99, v15, v224
	v_cvt_pk_bf16_f32 v156, v96, v97
	v_cvt_pk_bf16_f32 v157, v98, v99
	global_store_dwordx2 v252, v[156:157], s[72:73] offset:48
	v_mul_f32_e32 v96, v28, v224
	v_mul_f32_e32 v97, v29, v224
	v_mul_f32_e32 v98, v30, v224
	v_mul_f32_e32 v99, v31, v224
	v_cvt_pk_bf16_f32 v158, v96, v97
	v_cvt_pk_bf16_f32 v159, v98, v99
	global_store_dwordx2 v226, v[158:159], s[72:73] offset:48
